# cache policy: nt on the one-time bf16 weight-copy stores of the setup phase
# baseline (speedup 1.0000x reference)
; #define LAS __attribute__((address_space(3)))
; __device__ __forceinline__ int map_row_rt(int map, int n) { return map == 0 ? n : (map == 1 ? map_row<1>(n) : (map == 3 ? map_row<3>(n) : map_row<2>(n))); }
; __device__ __forceinline__ void titem_store(const TItem& t, int lane, const f32x2 (&v)[32], LAS unsigned* scr) {
;     ...
;     for (int j = 0; j < 8; ++j) { const int n = 8 * j + (lane >> 3); const LAS unsigned* sp = scr + (8 * c) * 33 + (n >> 1); const int sh = (n & 1) * 16;
;         unsigned e[8];
; #pragma unroll
;         for (int i = 0; i < 8; ++i) e[i] = (sp[i * 33] >> sh) & 0xffffu;
;         u32x4 o; o.x = e[0] | (e[1] << 16); o.y = e[2] | (e[3] << 16); o.z = e[4] | (e[5] << 16); o.w = e[6] | (e[7] << 16);
;         if (t.n0 + n < t.Npad) *(u32x4*)(t.WT + (size_t)map_row_rt(t.map, t.n0 + n) * t.K + t.k0 + 8 * c) = o; }
.LBB0_95:
	s_waitcnt lgkmcnt(0)
	v_lshrrev_b32_sdwa v139, v149, v139 dst_sel:WORD_1 dst_unused:UNUSED_PAD src0_sel:DWORD src1_sel:DWORD
	v_lshrrev_b32_e32 v138, v149, v138
	v_lshrrev_b32_sdwa v137, v149, v137 dst_sel:WORD_1 dst_unused:UNUSED_PAD src0_sel:DWORD src1_sel:DWORD
	v_lshrrev_b32_e32 v136, v149, v136
	v_lshrrev_b32_sdwa v135, v149, v135 dst_sel:WORD_1 dst_unused:UNUSED_PAD src0_sel:DWORD src1_sel:DWORD
	v_lshrrev_b32_e32 v134, v149, v134
	v_and_or_b32 v134, v134, s60, v135
	v_and_or_b32 v135, v136, s60, v137
	v_and_or_b32 v136, v138, s60, v139
	v_mad_i64_i32 v[138:139], s[42:43], v172, s22, 0
	v_lshrrev_b32_sdwa v68, v149, v141 dst_sel:WORD_1 dst_unused:UNUSED_PAD src0_sel:DWORD src1_sel:DWORD
	v_lshrrev_b32_e32 v140, v149, v140
	v_lshl_add_u64 v[138:139], v[138:139], 1, s[20:21]
	s_ashr_i32 s29, s28, 31
	v_and_or_b32 v137, v140, s60, v68
	v_lshl_add_u64 v[138:139], s[28:29], 1, v[138:139]
	v_lshlrev_b32_e32 v68, 1, v66
	v_lshl_add_u64 v[138:139], v[138:139], 0, v[68:69]
	global_store_dwordx4 v[138:139], v[134:137], off nt

; #define LAS __attribute__((address_space(3)))
; __device__ __forceinline__ int map_row_rt(int map, int n) { return map == 0 ? n : (map == 1 ? map_row<1>(n) : (map == 3 ? map_row<3>(n) : map_row<2>(n))); }
; __device__ __forceinline__ void titem_store(const TItem& t, int lane, const f32x2 (&v)[32], LAS unsigned* scr) {
;     ...
;     for (int j = 0; j < 8; ++j) { const int n = 8 * j + (lane >> 3); const LAS unsigned* sp = scr + (8 * c) * 33 + (n >> 1); const int sh = (n & 1) * 16;
;         unsigned e[8];
; #pragma unroll
;         for (int i = 0; i < 8; ++i) e[i] = (sp[i * 33] >> sh) & 0xffffu;
;         u32x4 o; o.x = e[0] | (e[1] << 16); o.y = e[2] | (e[3] << 16); o.z = e[4] | (e[5] << 16); o.w = e[6] | (e[7] << 16);
;         if (t.n0 + n < t.Npad) *(u32x4*)(t.WT + (size_t)map_row_rt(t.map, t.n0 + n) * t.K + t.k0 + 8 * c) = o; }
.LBB0_270:
	s_waitcnt lgkmcnt(0)
	v_lshrrev_b32_sdwa v139, v149, v139 dst_sel:WORD_1 dst_unused:UNUSED_PAD src0_sel:DWORD src1_sel:DWORD
	v_lshrrev_b32_e32 v138, v149, v138
	v_lshrrev_b32_sdwa v137, v149, v137 dst_sel:WORD_1 dst_unused:UNUSED_PAD src0_sel:DWORD src1_sel:DWORD
	v_lshrrev_b32_e32 v136, v149, v136
	v_lshrrev_b32_sdwa v135, v149, v135 dst_sel:WORD_1 dst_unused:UNUSED_PAD src0_sel:DWORD src1_sel:DWORD
	v_lshrrev_b32_e32 v134, v149, v134
	v_and_or_b32 v134, v134, s60, v135
	v_and_or_b32 v135, v136, s60, v137
	v_and_or_b32 v136, v138, s60, v139
	v_mad_i64_i32 v[138:139], s[42:43], v165, s62, 0
	v_lshrrev_b32_sdwa v68, v149, v141 dst_sel:WORD_1 dst_unused:UNUSED_PAD src0_sel:DWORD src1_sel:DWORD
	v_lshrrev_b32_e32 v140, v149, v140
	v_lshl_add_u64 v[138:139], v[138:139], 1, s[38:39]
	s_ashr_i32 s35, s34, 31
	v_and_or_b32 v137, v140, s60, v68
	v_lshl_add_u64 v[138:139], s[34:35], 1, v[138:139]
	v_lshlrev_b32_e32 v68, 1, v66
	v_lshl_add_u64 v[138:139], v[138:139], 0, v[68:69]
	global_store_dwordx4 v[138:139], v[134:137], off nt
